# s_setprio 2 around the L2 GEMM k-loop (a block in its MFMA loop wins issue arbitration over the co-resident block's prologue or epilogue)
# speedup vs baseline: 1.0067x; 1.0067x over previous
.LBB0_259:
	s_add_i32 s2, s6, s22
	s_mul_hi_i32 s3, s2, 0x8d3dcb09
	s_add_i32 s3, s3, s2
	s_lshr_b32 s4, s3, 31
	s_ashr_i32 s3, s3, 4
	s_add_i32 s3, s3, s4
	s_mul_i32 s4, s3, 29
	s_lshl_b32 s3, s3, 7
	s_sub_i32 s2, s2, s4
	s_lshl_b32 s2, s2, 7
	s_lshl_b32 s62, s3, 11
	s_add_u32 s54, s82, s62
	s_addc_u32 s55, s83, 0
	s_add_u32 s54, s54, 0x3000000
	s_addc_u32 s55, s55, 0
	s_lshl_b32 s62, s2, 11
	s_add_u32 s56, s60, s62
	s_addc_u32 s57, s61, 0
	s_add_u32 m0, s58, 0x0
	s_nop 0
	global_load_lds_dwordx4 v152, s[54:55]
	s_add_u32 m0, m0, 0x400
	s_nop 0
	global_load_lds_dwordx4 v153, s[54:55]
	s_add_u32 m0, m0, 0x400
	s_nop 0
	global_load_lds_dwordx4 v154, s[54:55]
	s_add_u32 m0, m0, 0x400
	s_nop 0
	global_load_lds_dwordx4 v155, s[54:55]
	s_add_u32 m0, m0, 0x3400
	s_nop 0
	global_load_lds_dwordx4 v152, s[56:57]
	s_add_u32 m0, m0, 0x400
	s_nop 0
	global_load_lds_dwordx4 v153, s[56:57]
	s_add_u32 m0, m0, 0x400
	s_nop 0
	global_load_lds_dwordx4 v154, s[56:57]
	s_add_u32 m0, m0, 0x400
	s_nop 0
	global_load_lds_dwordx4 v155, s[56:57]
	v_mov_b32_e32 v60, 0
	v_mov_b32_e32 v61, v60
	v_mov_b32_e32 v62, v60
	v_mov_b32_e32 v63, v60
	v_mov_b32_e32 v40, v60
	v_mov_b32_e32 v41, v60
	v_mov_b32_e32 v42, v60
	v_mov_b32_e32 v43, v60
	v_mov_b32_e32 v44, v60
	v_mov_b32_e32 v45, v60
	v_mov_b32_e32 v46, v60
	v_mov_b32_e32 v47, v60
	v_mov_b32_e32 v48, v60
	v_mov_b32_e32 v49, v60
	v_mov_b32_e32 v50, v60
	v_mov_b32_e32 v51, v60
	v_mov_b32_e32 v52, v60
	v_mov_b32_e32 v53, v60
	v_mov_b32_e32 v54, v60
	v_mov_b32_e32 v55, v60
	v_mov_b32_e32 v56, v60
	v_mov_b32_e32 v57, v60
	v_mov_b32_e32 v58, v60
	v_mov_b32_e32 v59, v60
	v_mov_b32_e32 v16, v60
	v_mov_b32_e32 v17, v60
	v_mov_b32_e32 v18, v60
	v_mov_b32_e32 v19, v60
	v_mov_b32_e32 v12, v60
	v_mov_b32_e32 v13, v60
	v_mov_b32_e32 v14, v60
	v_mov_b32_e32 v15, v60
	v_mov_b32_e32 v20, v60
	v_mov_b32_e32 v21, v60
	v_mov_b32_e32 v22, v60
	v_mov_b32_e32 v23, v60
	v_mov_b32_e32 v0, v60
	v_mov_b32_e32 v1, v60
	v_mov_b32_e32 v2, v60
	v_mov_b32_e32 v3, v60
	v_mov_b32_e32 v4, v60
	v_mov_b32_e32 v5, v60
	v_mov_b32_e32 v6, v60
	v_mov_b32_e32 v7, v60
	v_mov_b32_e32 v8, v60
	v_mov_b32_e32 v9, v60
	v_mov_b32_e32 v10, v60
	v_mov_b32_e32 v11, v60
	v_mov_b32_e32 v24, v60
	v_mov_b32_e32 v25, v60
	v_mov_b32_e32 v26, v60
	v_mov_b32_e32 v27, v60
	v_mov_b32_e32 v28, v60
	v_mov_b32_e32 v29, v60
	v_mov_b32_e32 v30, v60
	v_mov_b32_e32 v31, v60
	v_mov_b32_e32 v32, v60
	v_mov_b32_e32 v33, v60
	v_mov_b32_e32 v34, v60
	v_mov_b32_e32 v35, v60
	v_mov_b32_e32 v36, v60
	v_mov_b32_e32 v37, v60
	v_mov_b32_e32 v38, v60
	v_mov_b32_e32 v39, v60
	s_mov_b32 s59, 8
	s_waitcnt vmcnt(0)
	s_barrier
	s_setprio 2
.Lg2_loop:
	s_add_u32 s54, s54, 0x80
	s_addc_u32 s55, s55, 0
	s_add_u32 s56, s56, 0x80
	s_addc_u32 s57, s57, 0
	ds_read_b128 v[64:67], v156
	ds_read_b128 v[68:71], v158 offset:16384
	ds_read_b128 v[80:83], v159 offset:16384
	ds_read_b128 v[72:75], v157
	ds_read_b128 v[76:79], v158 offset:18432
	ds_read_b128 v[92:95], v159 offset:18432
	ds_read_b128 v[84:87], v158 offset:20480
	ds_read_b128 v[116:119], v159 offset:20480
	ds_read_b128 v[88:91], v158 offset:22528
	ds_read_b128 v[120:123], v159 offset:22528
	s_waitcnt lgkmcnt(8)
	v_mfma_f32_16x16x32_bf16 v[36:39], v[64:67], v[68:71], v[36:39]
	s_waitcnt lgkmcnt(5)
	v_mfma_f32_16x16x32_bf16 v[32:35], v[64:67], v[76:79], v[32:35]
	s_waitcnt lgkmcnt(3)
	s_add_u32 m0, s58, 0x8000
	v_mfma_f32_16x16x32_bf16 v[28:31], v[64:67], v[84:87], v[28:31]
	global_load_lds_dwordx4 v152, s[54:55]
	s_waitcnt lgkmcnt(1)
	v_mfma_f32_16x16x32_bf16 v[24:27], v[64:67], v[88:91], v[24:27]
	ds_read_b128 v[64:67], v156 offset:2048
	ds_read_b128 v[124:127], v157 offset:2048
	s_waitcnt lgkmcnt(1)
	v_mfma_f32_16x16x32_bf16 v[8:11], v[64:67], v[68:71], v[8:11]
	s_add_u32 m0, m0, 0x400
	v_mfma_f32_16x16x32_bf16 v[4:7], v[64:67], v[76:79], v[4:7]
	global_load_lds_dwordx4 v153, s[54:55]
	v_mfma_f32_16x16x32_bf16 v[0:3], v[64:67], v[84:87], v[0:3]
	v_mfma_f32_16x16x32_bf16 v[20:23], v[64:67], v[88:91], v[20:23]
	ds_read_b128 v[64:67], v156 offset:4096
	ds_read_b128 v[128:131], v157 offset:4096
	s_waitcnt lgkmcnt(1)
	s_add_u32 m0, m0, 0x400
	v_mfma_f32_16x16x32_bf16 v[12:15], v[64:67], v[68:71], v[12:15]
	global_load_lds_dwordx4 v154, s[54:55]
	v_mfma_f32_16x16x32_bf16 v[16:19], v[64:67], v[76:79], v[16:19]
	v_mfma_f32_16x16x32_bf16 v[56:59], v[64:67], v[84:87], v[56:59]
	s_add_u32 m0, m0, 0x400
	v_mfma_f32_16x16x32_bf16 v[52:55], v[64:67], v[88:91], v[52:55]
	global_load_lds_dwordx4 v155, s[54:55]
	ds_read_b128 v[64:67], v156 offset:6144
	ds_read_b128 v[132:135], v157 offset:6144
	s_waitcnt lgkmcnt(1)
	v_mfma_f32_16x16x32_bf16 v[48:51], v[64:67], v[68:71], v[48:51]
	v_mfma_f32_16x16x32_bf16 v[44:47], v[64:67], v[76:79], v[44:47]
	s_add_u32 m0, m0, 0x3400
	v_mfma_f32_16x16x32_bf16 v[40:43], v[64:67], v[84:87], v[40:43]
	global_load_lds_dwordx4 v152, s[56:57]
	v_mfma_f32_16x16x32_bf16 v[60:63], v[64:67], v[88:91], v[60:63]
	v_mfma_f32_16x16x32_bf16 v[36:39], v[72:75], v[80:83], v[36:39]
	s_add_u32 m0, m0, 0x400
	v_mfma_f32_16x16x32_bf16 v[32:35], v[72:75], v[92:95], v[32:35]
	global_load_lds_dwordx4 v153, s[56:57]
	v_mfma_f32_16x16x32_bf16 v[28:31], v[72:75], v[116:119], v[28:31]
	v_mfma_f32_16x16x32_bf16 v[24:27], v[72:75], v[120:123], v[24:27]
	s_add_u32 m0, m0, 0x400
	v_mfma_f32_16x16x32_bf16 v[8:11], v[124:127], v[80:83], v[8:11]
	global_load_lds_dwordx4 v154, s[56:57]
	v_mfma_f32_16x16x32_bf16 v[4:7], v[124:127], v[92:95], v[4:7]
	v_mfma_f32_16x16x32_bf16 v[0:3], v[124:127], v[116:119], v[0:3]
	s_add_u32 m0, m0, 0x400
	v_mfma_f32_16x16x32_bf16 v[20:23], v[124:127], v[120:123], v[20:23]
	global_load_lds_dwordx4 v155, s[56:57]
	v_mfma_f32_16x16x32_bf16 v[12:15], v[128:131], v[80:83], v[12:15]
	s_waitcnt lgkmcnt(0)
	v_mfma_f32_16x16x32_bf16 v[48:51], v[132:135], v[80:83], v[48:51]
	v_mfma_f32_16x16x32_bf16 v[16:19], v[128:131], v[92:95], v[16:19]
	v_mfma_f32_16x16x32_bf16 v[44:47], v[132:135], v[92:95], v[44:47]
	v_mfma_f32_16x16x32_bf16 v[56:59], v[128:131], v[116:119], v[56:59]
	v_mfma_f32_16x16x32_bf16 v[52:55], v[128:131], v[120:123], v[52:55]
	v_mfma_f32_16x16x32_bf16 v[40:43], v[132:135], v[116:119], v[40:43]
	v_mfma_f32_16x16x32_bf16 v[60:63], v[132:135], v[120:123], v[60:63]
	s_waitcnt vmcnt(0)
	s_barrier
	s_add_u32 s54, s54, 0x80
	s_addc_u32 s55, s55, 0
	s_add_u32 s56, s56, 0x80
	s_addc_u32 s57, s57, 0
	ds_read_b128 v[64:67], v156 offset:32768
	ds_read_b128 v[68:71], v158 offset:49152
	ds_read_b128 v[80:83], v159 offset:49152
	ds_read_b128 v[72:75], v157 offset:32768
	ds_read_b128 v[76:79], v158 offset:51200
	ds_read_b128 v[92:95], v159 offset:51200
	ds_read_b128 v[84:87], v158 offset:53248
	ds_read_b128 v[116:119], v159 offset:53248
	ds_read_b128 v[88:91], v158 offset:55296
	ds_read_b128 v[120:123], v159 offset:55296
	s_waitcnt lgkmcnt(8)
	v_mfma_f32_16x16x32_bf16 v[36:39], v[64:67], v[68:71], v[36:39]
	s_waitcnt lgkmcnt(5)
	v_mfma_f32_16x16x32_bf16 v[32:35], v[64:67], v[76:79], v[32:35]
	s_waitcnt lgkmcnt(3)
	s_add_u32 m0, s58, 0x0
	v_mfma_f32_16x16x32_bf16 v[28:31], v[64:67], v[84:87], v[28:31]
	global_load_lds_dwordx4 v152, s[54:55]
	s_waitcnt lgkmcnt(1)
	v_mfma_f32_16x16x32_bf16 v[24:27], v[64:67], v[88:91], v[24:27]
	ds_read_b128 v[64:67], v156 offset:34816
	ds_read_b128 v[124:127], v157 offset:34816
	s_waitcnt lgkmcnt(1)
	v_mfma_f32_16x16x32_bf16 v[8:11], v[64:67], v[68:71], v[8:11]
	s_add_u32 m0, m0, 0x400
	v_mfma_f32_16x16x32_bf16 v[4:7], v[64:67], v[76:79], v[4:7]
	global_load_lds_dwordx4 v153, s[54:55]
	v_mfma_f32_16x16x32_bf16 v[0:3], v[64:67], v[84:87], v[0:3]
	v_mfma_f32_16x16x32_bf16 v[20:23], v[64:67], v[88:91], v[20:23]
	ds_read_b128 v[64:67], v156 offset:36864
	ds_read_b128 v[128:131], v157 offset:36864
	s_waitcnt lgkmcnt(1)
	s_add_u32 m0, m0, 0x400
	v_mfma_f32_16x16x32_bf16 v[12:15], v[64:67], v[68:71], v[12:15]
	global_load_lds_dwordx4 v154, s[54:55]
	v_mfma_f32_16x16x32_bf16 v[16:19], v[64:67], v[76:79], v[16:19]
	v_mfma_f32_16x16x32_bf16 v[56:59], v[64:67], v[84:87], v[56:59]
	s_add_u32 m0, m0, 0x400
	v_mfma_f32_16x16x32_bf16 v[52:55], v[64:67], v[88:91], v[52:55]
	global_load_lds_dwordx4 v155, s[54:55]
	ds_read_b128 v[64:67], v156 offset:38912
	ds_read_b128 v[132:135], v157 offset:38912
	s_waitcnt lgkmcnt(1)
	v_mfma_f32_16x16x32_bf16 v[48:51], v[64:67], v[68:71], v[48:51]
	v_mfma_f32_16x16x32_bf16 v[44:47], v[64:67], v[76:79], v[44:47]
	s_add_u32 m0, m0, 0x3400
	v_mfma_f32_16x16x32_bf16 v[40:43], v[64:67], v[84:87], v[40:43]
	global_load_lds_dwordx4 v152, s[56:57]
	v_mfma_f32_16x16x32_bf16 v[60:63], v[64:67], v[88:91], v[60:63]
	v_mfma_f32_16x16x32_bf16 v[36:39], v[72:75], v[80:83], v[36:39]
	s_add_u32 m0, m0, 0x400
	v_mfma_f32_16x16x32_bf16 v[32:35], v[72:75], v[92:95], v[32:35]
	global_load_lds_dwordx4 v153, s[56:57]
	v_mfma_f32_16x16x32_bf16 v[28:31], v[72:75], v[116:119], v[28:31]
	v_mfma_f32_16x16x32_bf16 v[24:27], v[72:75], v[120:123], v[24:27]
	s_add_u32 m0, m0, 0x400
	v_mfma_f32_16x16x32_bf16 v[8:11], v[124:127], v[80:83], v[8:11]
	global_load_lds_dwordx4 v154, s[56:57]
	v_mfma_f32_16x16x32_bf16 v[4:7], v[124:127], v[92:95], v[4:7]
	v_mfma_f32_16x16x32_bf16 v[0:3], v[124:127], v[116:119], v[0:3]
	s_add_u32 m0, m0, 0x400
	v_mfma_f32_16x16x32_bf16 v[20:23], v[124:127], v[120:123], v[20:23]
	global_load_lds_dwordx4 v155, s[56:57]
	v_mfma_f32_16x16x32_bf16 v[12:15], v[128:131], v[80:83], v[12:15]
	s_waitcnt lgkmcnt(0)
	v_mfma_f32_16x16x32_bf16 v[48:51], v[132:135], v[80:83], v[48:51]
	v_mfma_f32_16x16x32_bf16 v[16:19], v[128:131], v[92:95], v[16:19]
	v_mfma_f32_16x16x32_bf16 v[44:47], v[132:135], v[92:95], v[44:47]
	v_mfma_f32_16x16x32_bf16 v[56:59], v[128:131], v[116:119], v[56:59]
	v_mfma_f32_16x16x32_bf16 v[52:55], v[128:131], v[120:123], v[52:55]
	v_mfma_f32_16x16x32_bf16 v[40:43], v[132:135], v[116:119], v[40:43]
	v_mfma_f32_16x16x32_bf16 v[60:63], v[132:135], v[120:123], v[60:63]
	s_waitcnt vmcnt(0)
	s_barrier
	s_add_i32 s59, s59, -1
	s_cmp_lg_u32 s59, 0
	s_cbranch_scc1 .Lg2_loop
	s_setprio 0
	s_nop 7
	s_nop 7
	s_movk_i32 s4, 0x3a00
	s_add_i32 s6, s6, s92
	v_add_u32_e32 v68, s3, v111
	s_ashr_i32 s3, s2, 31
	v_lshl_add_u64 v[64:65], s[2:3], 2, v[100:101]
	v_mad_i64_i32 v[66:67], s[2:3], v68, s4, v[64:65]
	global_store_dword v[66:67], v36, off sc1
	global_store_dword v[66:67], v32, off offset:64 sc1
	global_store_dword v[66:67], v28, off offset:128 sc1
	global_store_dword v[66:67], v24, off offset:192 sc1
	v_or_b32_e32 v24, 1, v68
	v_mad_i64_i32 v[66:67], s[2:3], v24, s4, v[64:65]
	v_or_b32_e32 v24, 2, v68
	global_store_dword v[66:67], v37, off sc1
	global_store_dword v[66:67], v33, off offset:64 sc1
	global_store_dword v[66:67], v29, off offset:128 sc1
	global_store_dword v[66:67], v25, off offset:192 sc1
	v_mad_i64_i32 v[24:25], s[2:3], v24, s4, v[64:65]
	global_store_dword v[24:25], v38, off sc1
	global_store_dword v[24:25], v34, off offset:64 sc1
	global_store_dword v[24:25], v30, off offset:128 sc1
	global_store_dword v[24:25], v26, off offset:192 sc1
	v_or_b32_e32 v24, 3, v68
	v_mad_i64_i32 v[24:25], s[2:3], v24, s4, v[64:65]
	global_store_dword v[24:25], v39, off sc1
	global_store_dword v[24:25], v35, off offset:64 sc1
	global_store_dword v[24:25], v31, off offset:128 sc1
	global_store_dword v[24:25], v27, off offset:192 sc1
	v_or_b32_e32 v24, 16, v68
	v_mad_i64_i32 v[24:25], s[2:3], v24, s4, v[64:65]
	global_store_dword v[24:25], v8, off sc1
	global_store_dword v[24:25], v4, off offset:64 sc1
	global_store_dword v[24:25], v0, off offset:128 sc1
	global_store_dword v[24:25], v20, off offset:192 sc1
	v_or_b32_e32 v0, 17, v68
	v_mad_i64_i32 v[24:25], s[2:3], v0, s4, v[64:65]
	v_or_b32_e32 v0, 18, v68
	global_store_dword v[24:25], v9, off sc1
	global_store_dword v[24:25], v5, off offset:64 sc1
	global_store_dword v[24:25], v1, off offset:128 sc1
	global_store_dword v[24:25], v21, off offset:192 sc1
	v_mad_i64_i32 v[0:1], s[2:3], v0, s4, v[64:65]
	global_store_dword v[0:1], v10, off sc1
	global_store_dword v[0:1], v6, off offset:64 sc1
	global_store_dword v[0:1], v2, off offset:128 sc1
	global_store_dword v[0:1], v22, off offset:192 sc1
	v_or_b32_e32 v0, 19, v68
	v_mad_i64_i32 v[0:1], s[2:3], v0, s4, v[64:65]
	global_store_dword v[0:1], v11, off sc1
	global_store_dword v[0:1], v7, off offset:64 sc1
	global_store_dword v[0:1], v3, off offset:128 sc1
	global_store_dword v[0:1], v23, off offset:192 sc1
	v_or_b32_e32 v0, 32, v68
	v_mad_i64_i32 v[0:1], s[2:3], v0, s4, v[64:65]
	global_store_dword v[0:1], v12, off sc1
	global_store_dword v[0:1], v16, off offset:64 sc1
	global_store_dword v[0:1], v56, off offset:128 sc1
	global_store_dword v[0:1], v52, off offset:192 sc1
	v_or_b32_e32 v0, 33, v68
	v_mad_i64_i32 v[0:1], s[2:3], v0, s4, v[64:65]
	global_store_dword v[0:1], v13, off sc1
	global_store_dword v[0:1], v17, off offset:64 sc1
	global_store_dword v[0:1], v57, off offset:128 sc1
	global_store_dword v[0:1], v53, off offset:192 sc1
	v_or_b32_e32 v0, 34, v68
	v_mad_i64_i32 v[0:1], s[2:3], v0, s4, v[64:65]
	global_store_dword v[0:1], v14, off sc1
	global_store_dword v[0:1], v18, off offset:64 sc1
	global_store_dword v[0:1], v58, off offset:128 sc1
	global_store_dword v[0:1], v54, off offset:192 sc1
	v_or_b32_e32 v0, 35, v68
	v_mad_i64_i32 v[0:1], s[2:3], v0, s4, v[64:65]
	global_store_dword v[0:1], v15, off sc1
	global_store_dword v[0:1], v19, off offset:64 sc1
	global_store_dword v[0:1], v59, off offset:128 sc1
	global_store_dword v[0:1], v55, off offset:192 sc1
	v_or_b32_e32 v0, 48, v68
	v_mad_i64_i32 v[0:1], s[2:3], v0, s4, v[64:65]
	global_store_dword v[0:1], v48, off sc1
	global_store_dword v[0:1], v44, off offset:64 sc1
	global_store_dword v[0:1], v40, off offset:128 sc1
	s_nop 4
	global_store_dword v[0:1], v60, off offset:192 sc1
	v_or_b32_e32 v0, 49, v68
	v_mad_i64_i32 v[0:1], s[2:3], v0, s4, v[64:65]
	global_store_dword v[0:1], v49, off sc1
	global_store_dword v[0:1], v45, off offset:64 sc1
	global_store_dword v[0:1], v41, off offset:128 sc1
	global_store_dword v[0:1], v61, off offset:192 sc1
	v_or_b32_e32 v0, 50, v68
	v_mad_i64_i32 v[0:1], s[2:3], v0, s4, v[64:65]
	global_store_dword v[0:1], v50, off sc1
	global_store_dword v[0:1], v46, off offset:64 sc1
	global_store_dword v[0:1], v42, off offset:128 sc1
	global_store_dword v[0:1], v62, off offset:192 sc1
	v_or_b32_e32 v0, 51, v68
	v_mad_i64_i32 v[0:1], s[2:3], v0, s4, v[64:65]
	s_cmp_ge_i32 s6, s21
	global_store_dword v[0:1], v51, off sc1
	global_store_dword v[0:1], v47, off offset:64 sc1
	global_store_dword v[0:1], v43, off offset:128 sc1
	global_store_dword v[0:1], v63, off offset:192 sc1
	s_cbranch_scc0 .LBB0_259
